# GEMM k-loop rescheduled by hand: A-major order at half boundaries, 4-deep B ring, every LDS fragment read issued >=6 MFMAs before use
# speedup vs baseline: 1.0211x; 1.0074x over previous
.LBB0_637:
	s_and_b64 s[2:3], s[8:9], exec
	v_readlane_b32 s2, v255, 26
	v_readlane_b32 s4, v255, 30
	v_readlane_b32 s3, v255, 27
	v_readlane_b32 s5, v255, 31
	s_cselect_b32 s24, s5, s3
	s_cselect_b32 s28, s4, s2
	v_readlane_b32 s2, v255, 24
	v_readlane_b32 s4, v255, 32
	v_readlane_b32 s3, v255, 25
	v_readlane_b32 s5, v255, 33
	s_cselect_b32 s29, s5, s3
	s_cselect_b32 s34, s4, s2
	v_readlane_b32 s2, v255, 23
	v_readlane_b32 s3, v255, 43
	s_cselect_b32 s14, s3, s2
	v_readlane_b32 s2, v255, 39
	s_cselect_b32 s39, s2, 0
	v_readlane_b32 s2, v255, 18
	v_readlane_b32 s3, v255, 40
	s_cselect_b32 s44, s3, s2
	s_lshl_b32 s45, s15, 8
	s_mul_i32 s2, s15, 0xfe
	s_add_i32 s45, s45, s39
	s_lshl_b32 s6, s47, 8
	s_add_i32 s4, s2, -1
	s_cmp_eq_u32 s44, 7
	s_cselect_b64 vcc, -1, 0
	s_and_b64 s[2:3], vcc, exec
	s_cselect_b32 s2, 0, s45
	s_cselect_b32 s40, s4, 0
	s_ashr_i32 s3, s2, 31
	v_mov_b32_e32 v175, v163
	s_mul_i32 s3, s3, s14
	s_mul_hi_u32 s4, s2, s14
	s_ashr_i32 s7, s6, 31
	s_add_i32 s3, s4, s3
	s_waitcnt vmcnt(1)
	v_ashrrev_i32_e32 v10, 6, v175
	s_waitcnt vmcnt(0)
	v_bfe_u32 v14, v175, 3, 3
	s_mul_i32 s2, s2, s14
	s_mul_i32 s4, s7, s14
	s_mul_hi_u32 s5, s6, s14
	v_lshl_or_b32 v6, v10, 5, v14
	s_add_i32 s5, s5, s4
	v_and_b32_e32 v0, 63, v175
	s_lshl_b64 s[2:3], s[2:3], 1
	s_mul_i32 s4, s6, s14
	s_add_u32 s2, s28, s2
	v_lshlrev_b32_e32 v176, 4, v0
	v_add_u32_e32 v0, s40, v6
	s_addc_u32 s3, s24, s3
	s_lshl_b64 s[4:5], s[4:5], 1
	v_med3_i32 v0, v0, 0, v211
	s_add_u32 s4, s34, s4
	v_cndmask_b32_e32 v0, v6, v0, vcc
	s_addc_u32 s5, s29, s5
	v_bfe_u32 v223, v175, 4, 2
	v_mad_u64_u32 v[166:167], s[28:29], v0, s14, 0
	v_xor_b32_e32 v4, v223, v175
	v_ashrrev_i32_e32 v2, 31, v0
	v_mov_b32_e32 v0, v167
	v_mad_u64_u32 v[2:3], s[28:29], v2, s14, v[0:1]
	v_lshlrev_b32_e32 v0, 3, v4
	v_lshlrev_b32_e32 v15, 2, v10
	v_and_b32_e32 v0, 56, v0
	v_lshlrev_b32_e32 v177, 12, v10
	v_lshlrev_b32_e32 v130, 1, v0
	v_ashrrev_i32_e32 v0, 31, v10
	v_or_b32_e32 v17, v176, v177
	v_or_b32_e32 v18, 1, v15
	v_and_b32_e32 v174, 3, v10
	v_mul_lo_u32 v16, v0, s14
	v_readfirstlane_b32 s15, v17
	v_add_u32_e32 v0, 0x8000, v17
	v_lshl_or_b32 v10, v18, 3, v14
	v_mov_b32_e32 v167, v2
	v_mad_u64_u32 v[168:169], s[28:29], v6, s14, 0
	s_mov_b32 m0, s15
	v_readfirstlane_b32 s15, v0
	v_add_u32_e32 v0, s40, v10
	v_lshl_add_u64 v[2:3], v[166:167], 1, s[2:3]
	v_mov_b32_e32 v131, v1
	v_add_u32_e32 v169, v169, v16
	v_med3_i32 v0, v0, 0, v211
	v_lshl_add_u64 v[4:5], v[2:3], 0, v[130:131]
	v_lshl_add_u64 v[6:7], v[168:169], 1, s[4:5]
	v_cndmask_b32_e32 v0, v10, v0, vcc
	v_lshl_add_u64 v[8:9], v[6:7], 0, v[130:131]
	global_load_lds_dwordx4 v[4:5], off
	s_mov_b32 m0, s15
	v_lshrrev_b32_e32 v4, 1, v10
	v_mad_u64_u32 v[170:171], s[28:29], v0, s14, 0
	global_load_lds_dwordx4 v[8:9], off
	v_xor_b32_e32 v8, v4, v175
	v_ashrrev_i32_e32 v4, 31, v0
	v_mov_b32_e32 v0, v171
	v_mad_u64_u32 v[4:5], s[28:29], v4, s14, v[0:1]
	v_lshlrev_b32_e32 v0, 3, v8
	v_lshlrev_b32_e32 v178, 10, v18
	v_mov_b32_e32 v171, v4
	v_and_b32_e32 v0, 56, v0
	v_mad_u64_u32 v[172:173], s[28:29], v10, s14, 0
	v_or_b32_e32 v18, v176, v178
	v_lshl_add_u64 v[4:5], v[170:171], 1, s[2:3]
	v_lshlrev_b32_e32 v132, 1, v0
	v_mov_b32_e32 v133, v1
	v_add_u32_e32 v173, v173, v16
	v_readfirstlane_b32 s15, v18
	v_add_u32_e32 v0, 0x8000, v18
	v_lshl_add_u64 v[8:9], v[4:5], 0, v[132:133]
	v_lshl_add_u64 v[10:11], v[172:173], 1, s[4:5]
	s_mov_b32 m0, s15
	v_readfirstlane_b32 s15, v0
	s_waitcnt lgkmcnt(0)
	v_lshl_add_u64 v[12:13], v[10:11], 0, v[132:133]
	global_load_lds_dwordx4 v[8:9], off
	s_mov_b32 m0, s15
	v_or_b32_e32 v19, 2, v15
	global_load_lds_dwordx4 v[12:13], off
	v_lshl_or_b32 v12, v19, 3, v14
	v_add_u32_e32 v0, s40, v12
	v_med3_i32 v0, v0, 0, v211
	v_cndmask_b32_e32 v0, v12, v0, vcc
	v_lshrrev_b32_e32 v8, 1, v12
	v_mad_u64_u32 v[154:155], s[28:29], v0, s14, 0
	v_xor_b32_e32 v13, v8, v175
	v_ashrrev_i32_e32 v8, 31, v0
	v_mov_b32_e32 v0, v155
	v_mad_u64_u32 v[8:9], s[28:29], v8, s14, v[0:1]
	v_lshlrev_b32_e32 v0, 3, v13
	v_lshlrev_b32_e32 v179, 10, v19
	v_mov_b32_e32 v155, v8
	v_and_b32_e32 v0, 56, v0
	v_or_b32_e32 v19, v176, v179
	v_lshl_add_u64 v[8:9], v[154:155], 1, s[2:3]
	v_lshlrev_b32_e32 v0, 1, v0
	v_readfirstlane_b32 s15, v19
	v_lshl_add_u64 v[8:9], v[8:9], 0, v[0:1]
	v_mad_u64_u32 v[156:157], s[28:29], v12, s14, 0
	s_mov_b32 m0, s15
	v_add_u32_e32 v157, v157, v16
	global_load_lds_dwordx4 v[8:9], off
	v_add_u32_e32 v8, 0x8000, v19
	v_lshl_add_u64 v[12:13], v[156:157], 1, s[4:5]
	v_readfirstlane_b32 s15, v8
	v_lshl_add_u64 v[12:13], v[12:13], 0, v[0:1]
	s_mov_b32 m0, s15
	v_or_b32_e32 v15, 3, v15
	global_load_lds_dwordx4 v[12:13], off
	v_lshl_or_b32 v12, v15, 3, v14
	v_add_u32_e32 v8, s40, v12
	v_med3_i32 v8, v8, 0, v211
	v_cndmask_b32_e32 v8, v12, v8, vcc
	v_lshrrev_b32_e32 v9, 1, v12
	v_mad_u64_u32 v[158:159], s[28:29], v8, s14, 0
	v_xor_b32_e32 v13, v9, v175
	v_ashrrev_i32_e32 v9, 31, v8
	v_mov_b32_e32 v8, v159
	v_mad_u64_u32 v[8:9], s[28:29], v9, s14, v[8:9]
	v_lshlrev_b32_e32 v13, 3, v13
	v_lshlrev_b32_e32 v180, 10, v15
	v_mov_b32_e32 v159, v8
	v_and_b32_e32 v13, 56, v13
	v_or_b32_e32 v14, v176, v180
	v_lshl_add_u64 v[8:9], v[158:159], 1, s[2:3]
	v_lshlrev_b32_e32 v160, 1, v13
	v_mov_b32_e32 v161, v1
	v_readfirstlane_b32 s15, v14
	v_lshl_add_u64 v[8:9], v[8:9], 0, v[160:161]
	v_mad_u64_u32 v[164:165], s[28:29], v12, s14, 0
	s_mov_b32 m0, s15
	v_add_u32_e32 v165, v165, v16
	global_load_lds_dwordx4 v[8:9], off
	v_add_u32_e32 v8, 0x8000, v14
	s_cmpk_gt_u32 s14, 0x7f
	v_lshl_add_u64 v[12:13], v[164:165], 1, s[4:5]
	v_readfirstlane_b32 s15, v8
	s_cselect_b32 s34, 0x80, 0
	v_add_u32_e32 v8, 0x10000, v17
	v_lshl_add_u64 v[12:13], v[12:13], 0, v[160:161]
	s_mov_b32 m0, s15
	v_lshl_add_u64 v[2:3], v[2:3], 0, s[34:35]
	v_readfirstlane_b32 s15, v8
	global_load_lds_dwordx4 v[12:13], off
	v_lshl_add_u64 v[2:3], v[2:3], 0, v[130:131]
	s_mov_b32 m0, s15
	v_mov_b32_e32 v127, 0
	v_mov_b32_e32 v128, 0
	v_mov_b32_e32 v129, 0
	v_mov_b32_e32 v122, 0
	v_mov_b32_e32 v123, 0
	v_mov_b32_e32 v124, 0
	v_mov_b32_e32 v125, 0
	v_mov_b32_e32 v118, 0
	v_mov_b32_e32 v119, 0
	v_mov_b32_e32 v120, 0
	v_mov_b32_e32 v121, 0
	v_mov_b32_e32 v114, 0
	v_mov_b32_e32 v115, 0
	v_mov_b32_e32 v116, 0
	v_mov_b32_e32 v117, 0
	v_mov_b32_e32 v110, 0
	v_mov_b32_e32 v111, 0
	v_mov_b32_e32 v112, 0
	v_mov_b32_e32 v113, 0
	v_mov_b32_e32 v106, 0
	v_mov_b32_e32 v107, 0
	v_mov_b32_e32 v108, 0
	v_mov_b32_e32 v109, 0
	v_mov_b32_e32 v102, 0
	v_mov_b32_e32 v103, 0
	v_mov_b32_e32 v104, 0
	v_mov_b32_e32 v105, 0
	v_mov_b32_e32 v98, 0
	v_mov_b32_e32 v99, 0
	v_mov_b32_e32 v100, 0
	v_mov_b32_e32 v101, 0
	v_mov_b32_e32 v94, 0
	v_mov_b32_e32 v95, 0
	v_mov_b32_e32 v96, 0
	v_mov_b32_e32 v97, 0
	v_mov_b32_e32 v90, 0
	v_mov_b32_e32 v91, 0
	v_mov_b32_e32 v92, 0
	v_mov_b32_e32 v93, 0
	v_mov_b32_e32 v86, 0
	v_mov_b32_e32 v87, 0
	v_mov_b32_e32 v88, 0
	v_mov_b32_e32 v89, 0
	v_mov_b32_e32 v82, 0
	v_mov_b32_e32 v83, 0
	v_mov_b32_e32 v84, 0
	v_mov_b32_e32 v85, 0
	v_mov_b32_e32 v78, 0
	v_mov_b32_e32 v79, 0
	v_mov_b32_e32 v80, 0
	v_mov_b32_e32 v81, 0
	v_mov_b32_e32 v74, 0
	v_mov_b32_e32 v75, 0
	v_mov_b32_e32 v76, 0
	v_mov_b32_e32 v77, 0
	v_mov_b32_e32 v70, 0
	v_mov_b32_e32 v71, 0
	v_mov_b32_e32 v72, 0
	v_mov_b32_e32 v73, 0
	v_mov_b32_e32 v66, 0
	v_mov_b32_e32 v67, 0
	v_mov_b32_e32 v68, 0
	v_mov_b32_e32 v69, 0
	v_mov_b32_e32 v62, 0
	v_mov_b32_e32 v63, 0
	v_mov_b32_e32 v64, 0
	v_mov_b32_e32 v65, 0
	v_mov_b32_e32 v58, 0
	v_mov_b32_e32 v59, 0
	v_mov_b32_e32 v60, 0
	v_mov_b32_e32 v61, 0
	v_mov_b32_e32 v54, 0
	v_mov_b32_e32 v55, 0
	v_mov_b32_e32 v56, 0
	v_mov_b32_e32 v57, 0
	v_mov_b32_e32 v50, 0
	v_mov_b32_e32 v51, 0
	v_mov_b32_e32 v52, 0
	v_mov_b32_e32 v53, 0
	v_mov_b32_e32 v46, 0
	v_mov_b32_e32 v47, 0
	v_mov_b32_e32 v48, 0
	v_mov_b32_e32 v49, 0
	v_mov_b32_e32 v42, 0
	v_mov_b32_e32 v43, 0
	v_mov_b32_e32 v44, 0
	v_mov_b32_e32 v45, 0
	v_mov_b32_e32 v34, 0
	v_mov_b32_e32 v35, 0
	v_mov_b32_e32 v36, 0
	v_mov_b32_e32 v37, 0
	v_mov_b32_e32 v30, 0
	v_mov_b32_e32 v31, 0
	v_mov_b32_e32 v32, 0
	v_mov_b32_e32 v33, 0
	v_mov_b32_e32 v38, 0
	v_mov_b32_e32 v39, 0
	v_mov_b32_e32 v40, 0
	v_mov_b32_e32 v41, 0
	v_mov_b32_e32 v26, 0
	v_mov_b32_e32 v27, 0
	v_mov_b32_e32 v28, 0
	v_mov_b32_e32 v29, 0
	v_mov_b32_e32 v22, 0
	v_mov_b32_e32 v23, 0
	v_mov_b32_e32 v24, 0
	v_mov_b32_e32 v25, 0
	v_mov_b32_e32 v19, 0
	v_mov_b32_e32 v20, 0
	v_mov_b32_e32 v21, 0
	v_mov_b32_e32 v14, 0
	v_mov_b32_e32 v15, 0
	v_mov_b32_e32 v16, 0
	v_mov_b32_e32 v12, 0
	v_mov_b32_e32 v13, 0
	s_waitcnt vmcnt(0)
	s_waitcnt vmcnt(0) lgkmcnt(0)
	s_barrier
	global_load_lds_dwordx4 v[2:3], off
	v_add_u32_e32 v2, 0x18000, v17
	v_lshl_add_u64 v[6:7], v[6:7], 0, s[34:35]
	v_readfirstlane_b32 s15, v2
	v_lshl_add_u64 v[6:7], v[6:7], 0, v[130:131]
	s_mov_b32 m0, s15
	v_lshl_add_u64 v[2:3], v[4:5], 0, s[34:35]
	global_load_lds_dwordx4 v[6:7], off
	v_add_u32_e32 v6, 0x10000, v18
	v_lshl_add_u64 v[2:3], v[2:3], 0, v[132:133]
	v_readfirstlane_b32 s15, v6
	s_mov_b32 m0, s15
	v_lshl_add_u64 v[4:5], v[10:11], 0, s[34:35]
	global_load_lds_dwordx4 v[2:3], off
	v_add_u32_e32 v2, 0x18000, v18
	v_lshl_add_u64 v[4:5], v[4:5], 0, v[132:133]
	v_readfirstlane_b32 s15, v2
	s_mov_b32 m0, s15
	v_and_b32_e32 v134, 15, v175
	global_load_lds_dwordx4 v[4:5], off
	v_ashrrev_i32_e32 v2, 1, v175
	s_movk_i32 s15, 0xff80
	v_mov_b32_e32 v5, 0
	v_and_or_b32 v225, v2, s15, v134
	v_lshlrev_b32_e32 v224, 6, v174
	s_cmp_lt_u32 s14, 64
	v_readlane_b32 s51, v255, 37
	v_readlane_b32 s52, v255, 38
	s_cbranch_scc1 .Lgemm_skip_zero_a
	v_lshrrev_b32_e32 v10, 1, v134
	v_or_b32_e32 v2, v224, v134
	v_lshlrev_b32_e32 v182, 7, v2
	v_xor_b32_e32 v2, v223, v10
	v_lshlrev_b32_e32 v181, 7, v225
	v_lshlrev_b32_e32 v183, 4, v2
	v_or_b32_e32 v11, v181, v183
	v_or_b32_e32 v244, v182, v183
	v_lshl_add_u64 v[2:3], s[4:5], 0, v[132:133]
	v_lshl_add_u64 v[4:5], s[2:3], 0, v[132:133]
	v_lshl_add_u64 v[6:7], s[4:5], 0, v[130:131]
	v_lshl_add_u64 v[8:9], s[2:3], 0, v[130:131]
	ds_read_b128 v[150:153], v11
	ds_read_b128 v[146:149], v11 offset:2048
	ds_read_b128 v[142:145], v244 offset:32768
	ds_read_b128 v[138:141], v244 offset:34816
	ds_read_b128 v[134:137], v244 offset:36864
	ds_read_b128 v[200:203], v11 offset:4096
	ds_read_b128 v[130:133], v244 offset:38912
	ds_read_b128 v[236:239], v11 offset:6144
	s_lshr_b32 s14, s14, 6
	v_bitop3_b32 v10, v223, v10, 4 bitop3:0x36
	v_mov_b32_e32 v126, 0
	s_add_i32 s15, s14, -1
	v_lshlrev_b32_e32 v184, 4, v10
	v_lshl_add_u64 v[166:167], v[166:167], 1, v[8:9]
	v_lshl_add_u64 v[168:169], v[168:169], 1, v[6:7]
	v_lshl_add_u64 v[170:171], v[170:171], 1, v[4:5]
	v_lshl_add_u64 v[172:173], v[172:173], 1, v[2:3]
	s_mov_b32 s24, 0
	s_mov_b32 s28, 0
	v_mov_b32_e32 v18, v126
	v_mov_b32_e32 v17, v126
	v_mov_b32_e32 v10, v126
	v_mov_b32_e32 v11, v126
	v_mov_b32_e32 v6, v126
	v_mov_b32_e32 v7, v126
	v_mov_b32_e32 v8, v126
	v_mov_b32_e32 v9, v126
	v_mov_b32_e32 v2, v126
	v_mov_b32_e32 v3, v126
	v_mov_b32_e32 v4, v126
	v_mov_b32_e32 v5, v126
.LBB0_639:
	s_add_i32 s41, s28, 1
	s_cmp_lt_u32 s41, s14
	s_cselect_b32 s29, s41, s28
	s_and_b32 s46, s24, 0x10000
	s_lshl_b32 s34, s29, 6
	s_xor_b32 s50, s46, 0x10000
	s_lshl_b64 s[42:43], s[34:35], 1
	s_add_u32 s48, s2, s42
	s_addc_u32 s49, s3, s43
	v_bitop3_b32 v226, s24, v176, v212 bitop3:0xce
	s_add_u32 s42, s4, s42
	v_add_u32_e32 v185, s46, v181
	s_waitcnt lgkmcnt(5)
	v_mfma_f32_16x16x32_bf16 v[126:129], v[142:145], v[150:153], v[126:129]
	s_addc_u32 s43, s5, s43
	v_lshl_add_u64 v[186:187], v[154:155], 1, s[48:49]
	v_mov_b32_e32 v161, v1
	v_add_u32_e32 v227, v185, v183
	v_mfma_f32_16x16x32_bf16 v[110:113], v[142:145], v[146:149], v[110:113]
	v_lshl_add_u64 v[186:187], v[186:187], 0, v[0:1]
	v_lshl_add_u64 v[240:241], v[156:157], 1, s[42:43]
	s_waitcnt lgkmcnt(4)
	v_mfma_f32_16x16x32_bf16 v[122:125], v[138:141], v[150:153], v[122:125]
	s_add_i32 s28, s28, 2
	s_min_i32 s28, s28, s15
	s_lshl_b32 s28, s28, 6
	v_mfma_f32_16x16x32_bf16 v[106:109], v[138:141], v[146:149], v[106:109]
	v_add_u32_e32 v242, v226, v179
	v_lshl_add_u64 v[240:241], v[240:241], 0, v[0:1]
	v_readfirstlane_b32 s29, v242
	s_waitcnt lgkmcnt(3)
	v_mfma_f32_16x16x32_bf16 v[118:121], v[134:137], v[150:153], v[118:121]
	v_add_u32_e32 v242, 0x8000, v242
	s_mov_b32 m0, s29
	v_readfirstlane_b32 s29, v242
	v_mfma_f32_16x16x32_bf16 v[102:105], v[134:137], v[146:149], v[102:105]
	global_load_lds_dwordx4 v[186:187], off
	s_mov_b32 m0, s29
	s_waitcnt lgkmcnt(1)
	v_mfma_f32_16x16x32_bf16 v[114:117], v[130:133], v[150:153], v[114:117]
	ds_read_b128 v[150:153], v227 offset:8192
	global_load_lds_dwordx4 v[240:241], off
	v_mfma_f32_16x16x32_bf16 v[98:101], v[130:133], v[146:149], v[98:101]
	ds_read_b128 v[146:149], v227 offset:10240
	v_lshl_add_u64 v[244:245], v[158:159], 1, s[48:49]
	v_lshl_add_u64 v[246:247], v[164:165], 1, s[42:43]
	v_mfma_f32_16x16x32_bf16 v[94:97], v[142:145], v[200:203], v[94:97]
	v_lshl_add_u64 v[244:245], v[244:245], 0, v[160:161]
	v_lshl_add_u64 v[246:247], v[246:247], 0, v[160:161]
	v_add_u32_e32 v161, v226, v180
	v_mfma_f32_16x16x32_bf16 v[90:93], v[138:141], v[200:203], v[90:93]
	v_readfirstlane_b32 s29, v161
	s_mov_b32 m0, s29
	v_mfma_f32_16x16x32_bf16 v[86:89], v[134:137], v[200:203], v[86:89]
	global_load_lds_dwordx4 v[244:245], off
	v_add_u32_e32 v242, 0x8000, v161
	v_mfma_f32_16x16x32_bf16 v[82:85], v[130:133], v[200:203], v[82:85]
	ds_read_b128 v[200:203], v227 offset:12288
	v_readfirstlane_b32 s29, v242
	s_mov_b32 m0, s29
	v_bitop3_b32 v243, s24, v182, v212 bitop3:0xce
	s_waitcnt lgkmcnt(3)
	v_mfma_f32_16x16x32_bf16 v[78:81], v[142:145], v[236:239], v[78:81]
	global_load_lds_dwordx4 v[246:247], off
	v_add_u32_e32 v233, v243, v183
	v_mfma_f32_16x16x32_bf16 v[74:77], v[138:141], v[236:239], v[74:77]
	v_add3_u32 v187, s46, v177, v176
	v_add3_u32 v231, s46, v178, v176
	v_mfma_f32_16x16x32_bf16 v[70:73], v[134:137], v[236:239], v[70:73]
	v_or_b32_e32 v228, s46, v182
	s_ashr_i32 s29, s28, 31
	v_mfma_f32_16x16x32_bf16 v[66:69], v[130:133], v[236:239], v[66:69]
	ds_read_b128 v[236:239], v227 offset:14336
	v_add_u32_e32 v230, 0x8000, v187
	v_add_u32_e32 v232, 0x8000, v231
	s_waitcnt lgkmcnt(3)
	v_mfma_f32_16x16x32_bf16 v[62:65], v[142:145], v[150:153], v[62:65]
	v_add3_u32 v234, s50, v181, v183
	v_add_u32_e32 v228, v228, v184
	v_mfma_f32_16x16x32_bf16 v[58:61], v[138:141], v[150:153], v[58:61]
	v_add_u32_e32 v229, v185, v184
	v_mfma_f32_16x16x32_bf16 v[54:57], v[134:137], v[150:153], v[54:57]
	v_mfma_f32_16x16x32_bf16 v[50:53], v[130:133], v[150:153], v[50:53]
	ds_read_b128 v[150:153], v229
	s_waitcnt lgkmcnt(3)
	v_mfma_f32_16x16x32_bf16 v[46:49], v[142:145], v[146:149], v[46:49]
	v_mfma_f32_16x16x32_bf16 v[42:45], v[138:141], v[146:149], v[42:45]
	v_mfma_f32_16x16x32_bf16 v[34:37], v[134:137], v[146:149], v[34:37]
	v_mfma_f32_16x16x32_bf16 v[30:33], v[130:133], v[146:149], v[30:33]
	ds_read_b128 v[146:149], v229 offset:2048
	s_waitcnt lgkmcnt(3)
	v_mfma_f32_16x16x32_bf16 v[38:41], v[142:145], v[200:203], v[38:41]
	s_waitcnt lgkmcnt(2)
	v_mfma_f32_16x16x32_bf16 v[14:17], v[142:145], v[236:239], v[14:17]
	ds_read_b128 v[142:145], v228 offset:32768
	v_mfma_f32_16x16x32_bf16 v[26:29], v[138:141], v[200:203], v[26:29]
	v_mfma_f32_16x16x32_bf16 v[10:13], v[138:141], v[236:239], v[10:13]
	ds_read_b128 v[138:141], v228 offset:34816
	v_mfma_f32_16x16x32_bf16 v[22:25], v[134:137], v[200:203], v[22:25]
	v_mfma_f32_16x16x32_bf16 v[6:9], v[134:137], v[236:239], v[6:9]
	ds_read_b128 v[134:137], v228 offset:36864
	v_mfma_f32_16x16x32_bf16 v[18:21], v[130:133], v[200:203], v[18:21]
	ds_read_b128 v[200:203], v229 offset:4096
	v_mfma_f32_16x16x32_bf16 v[2:5], v[130:133], v[236:239], v[2:5]
	ds_read_b128 v[130:133], v228 offset:38912
	ds_read_b128 v[236:239], v229 offset:6144
	s_waitcnt lgkmcnt(5)
	v_mfma_f32_16x16x32_bf16 v[126:129], v[142:145], v[150:153], v[126:129]
	v_mfma_f32_16x16x32_bf16 v[110:113], v[142:145], v[146:149], v[110:113]
	s_waitcnt lgkmcnt(4)
	v_mfma_f32_16x16x32_bf16 v[122:125], v[138:141], v[150:153], v[122:125]
	v_mfma_f32_16x16x32_bf16 v[106:109], v[138:141], v[146:149], v[106:109]
	s_waitcnt lgkmcnt(3)
	v_mfma_f32_16x16x32_bf16 v[118:121], v[134:137], v[150:153], v[118:121]
	v_mfma_f32_16x16x32_bf16 v[102:105], v[134:137], v[146:149], v[102:105]
	s_waitcnt lgkmcnt(1)
	v_mfma_f32_16x16x32_bf16 v[114:117], v[130:133], v[150:153], v[114:117]
	ds_read_b128 v[150:153], v229 offset:8192
	v_mfma_f32_16x16x32_bf16 v[98:101], v[130:133], v[146:149], v[98:101]
	ds_read_b128 v[146:149], v229 offset:10240
	v_mfma_f32_16x16x32_bf16 v[94:97], v[142:145], v[200:203], v[94:97]
	v_mfma_f32_16x16x32_bf16 v[90:93], v[138:141], v[200:203], v[90:93]
	v_mfma_f32_16x16x32_bf16 v[86:89], v[134:137], v[200:203], v[86:89]
	v_mfma_f32_16x16x32_bf16 v[82:85], v[130:133], v[200:203], v[82:85]
	ds_read_b128 v[200:203], v229 offset:12288
	s_waitcnt lgkmcnt(3)
	v_mfma_f32_16x16x32_bf16 v[78:81], v[142:145], v[236:239], v[78:81]
	v_mfma_f32_16x16x32_bf16 v[74:77], v[138:141], v[236:239], v[74:77]
	v_mfma_f32_16x16x32_bf16 v[70:73], v[134:137], v[236:239], v[70:73]
	s_lshl_b64 s[28:29], s[28:29], 1
	v_readfirstlane_b32 s34, v187
	v_mfma_f32_16x16x32_bf16 v[66:69], v[130:133], v[236:239], v[66:69]
	ds_read_b128 v[236:239], v229 offset:14336
	s_mov_b32 m0, s34
	v_readfirstlane_b32 s34, v230
	s_waitcnt lgkmcnt(3)
	v_mfma_f32_16x16x32_bf16 v[62:65], v[142:145], v[150:153], v[62:65]
	v_mfma_f32_16x16x32_bf16 v[58:61], v[138:141], v[150:153], v[58:61]
	v_mfma_f32_16x16x32_bf16 v[54:57], v[134:137], v[150:153], v[54:57]
	s_waitcnt vmcnt(0)
	v_mfma_f32_16x16x32_bf16 v[50:53], v[130:133], v[150:153], v[50:53]
	s_waitcnt vmcnt(0) lgkmcnt(0)
	s_barrier
	ds_read_b128 v[150:153], v234
	v_mfma_f32_16x16x32_bf16 v[46:49], v[142:145], v[146:149], v[46:49]
	v_lshl_add_u64 v[240:241], v[166:167], 0, s[28:29]
	v_lshl_add_u64 v[244:245], v[168:169], 0, s[28:29]
	global_load_lds_dwordx4 v[240:241], off
	v_mfma_f32_16x16x32_bf16 v[42:45], v[138:141], v[146:149], v[42:45]
	s_mov_b32 m0, s34
	v_mfma_f32_16x16x32_bf16 v[34:37], v[134:137], v[146:149], v[34:37]
	global_load_lds_dwordx4 v[244:245], off
	v_mfma_f32_16x16x32_bf16 v[30:33], v[130:133], v[146:149], v[30:33]
	ds_read_b128 v[146:149], v234 offset:2048
	v_lshl_add_u64 v[246:247], v[170:171], 0, s[28:29]
	v_lshl_add_u64 v[242:243], v[172:173], 0, s[28:29]
	v_readfirstlane_b32 s28, v231
	v_mfma_f32_16x16x32_bf16 v[38:41], v[142:145], v[200:203], v[38:41]
	s_mov_b32 m0, s28
	v_readfirstlane_b32 s28, v232
	v_mfma_f32_16x16x32_bf16 v[14:17], v[142:145], v[236:239], v[14:17]
	ds_read_b128 v[142:145], v233 offset:32768
	global_load_lds_dwordx4 v[246:247], off
	s_mov_b32 m0, s28
	v_mfma_f32_16x16x32_bf16 v[26:29], v[138:141], v[200:203], v[26:29]
	v_mfma_f32_16x16x32_bf16 v[10:13], v[138:141], v[236:239], v[10:13]
	ds_read_b128 v[138:141], v233 offset:34816
	global_load_lds_dwordx4 v[242:243], off
	v_mfma_f32_16x16x32_bf16 v[22:25], v[134:137], v[200:203], v[22:25]
	v_mfma_f32_16x16x32_bf16 v[6:9], v[134:137], v[236:239], v[6:9]
	ds_read_b128 v[134:137], v233 offset:36864
	v_mfma_f32_16x16x32_bf16 v[18:21], v[130:133], v[200:203], v[18:21]
	ds_read_b128 v[200:203], v234 offset:4096
	v_mfma_f32_16x16x32_bf16 v[2:5], v[130:133], v[236:239], v[2:5]
	ds_read_b128 v[130:133], v233 offset:38912
	ds_read_b128 v[236:239], v234 offset:6144
	s_add_i32 s24, s24, 0x10000
	s_cmp_eq_u32 s14, s41
	s_mov_b32 s28, s41
	s_cbranch_scc0 .LBB0_639
